# staging waves: buffer-write and partial-sum LDS bursts spread out with short sleeps so the scan waves' reads are not queued behind them
# speedup vs baseline: 1.0176x; 1.0030x over previous
.Lsc_gf_go1:
	ds_read_b32 v185, v183
	ds_read_b32 v186, v183 offset:256
	ds_read_b32 v187, v183 offset:512
	s_waitcnt lgkmcnt(0)
	v_and_b32_e32 v185, v174, v185
	v_and_b32_e32 v186, v175, v186
	v_and_b32_e32 v187, v176, v187
	v_add_f32_e32 v185, v185, v186
	v_add_f32_e32 v185, v185, v187
	v_fma_f32 v124, v124, s14, v185
	v_fma_f32 v125, v125, s14, v185
	v_fma_f32 v126, v126, s14, v185
	v_fma_f32 v127, v127, s14, v185
	v_fma_f32 v128, v128, s14, v185
	v_fma_f32 v129, v129, s14, v185
	v_fma_f32 v130, v130, s14, v185
	v_fma_f32 v131, v131, s14, v185
	v_exp_f32_e64 v188, -v185
	v_exp_f32_e64 v124, -v124
	v_exp_f32_e64 v125, -v125
	v_exp_f32_e64 v126, -v126
	v_exp_f32_e64 v127, -v127
	v_exp_f32_e64 v128, -v128
	v_exp_f32_e64 v129, -v129
	v_exp_f32_e64 v130, -v130
	v_exp_f32_e64 v131, -v131
	s_nop 0
	ds_write_b32 v155, v188
	ds_write_b32 v155, v124 offset:256
	ds_write_b32 v155, v125 offset:512
	ds_write_b32 v155, v126 offset:768
	ds_write_b32 v155, v127 offset:1024
	ds_write_b32 v155, v128 offset:1280
	ds_write_b32 v155, v129 offset:1536
	ds_write_b32 v155, v130 offset:1792
	ds_write_b32 v155, v131 offset:2048
	v_mov_b32_e32 v161, v131
	s_waitcnt lgkmcnt(0)
	ds_read_b128 v[64:67], v153 offset:2048
	ds_read_b128 v[68:71], v153 offset:2176
	ds_read_b128 v[116:119], v153 offset:2304
	ds_read_b128 v[120:123], v153 offset:2432
	s_waitcnt lgkmcnt(0)
	v_rcp_f32_e32 v124, v116
	v_rcp_f32_e32 v125, v117
	v_rcp_f32_e32 v126, v118
	v_rcp_f32_e32 v127, v119
	v_rcp_f32_e32 v128, v120
	v_rcp_f32_e32 v129, v121
	v_rcp_f32_e32 v130, v122
	v_rcp_f32_e32 v131, v123
	s_nop 1
	v_pk_mul_f32 v[72:73], v[72:73], v[124:125]
	v_pk_mul_f32 v[80:81], v[80:81], v[124:125]
	v_pk_mul_f32 v[88:89], v[88:89], v[64:65]
	v_pk_mul_f32 v[96:97], v[96:97], v[116:117]
	v_pk_mul_f32 v[74:75], v[74:75], v[126:127]
	v_pk_mul_f32 v[82:83], v[82:83], v[126:127]
	v_pk_mul_f32 v[90:91], v[90:91], v[66:67]
	v_pk_mul_f32 v[98:99], v[98:99], v[118:119]
	v_pk_mul_f32 v[76:77], v[76:77], v[128:129]
	v_pk_mul_f32 v[84:85], v[84:85], v[128:129]
	v_pk_mul_f32 v[92:93], v[92:93], v[68:69]
	v_pk_mul_f32 v[100:101], v[100:101], v[120:121]
	v_pk_mul_f32 v[78:79], v[78:79], v[130:131]
	v_pk_mul_f32 v[86:87], v[86:87], v[130:131]
	v_pk_mul_f32 v[94:95], v[94:95], v[70:71]
	v_pk_mul_f32 v[102:103], v[102:103], v[122:123]
	global_load_dwordx2 v[28:29], v5, s[36:37]
	global_load_dwordx2 v[30:31], v5, s[36:37] offset:64
	global_load_dwordx2 v[32:33], v5, s[38:39]
	global_load_dwordx2 v[34:35], v5, s[38:39] offset:64
	global_load_dwordx2 v[36:37], v5, s[40:41]
	global_load_dwordx2 v[38:39], v5, s[40:41] offset:64
	global_load_dwordx2 v[40:41], v5, s[42:43]
	global_load_dwordx2 v[42:43], v5, s[42:43] offset:64
	global_load_dword v44, v6, s[46:47]
	global_load_dword v45, v9, s[44:45]
	v_add_u32_e32 v5, s54, v5
	v_add_u32_e32 v6, s55, v6
	v_add_u32_e32 v9, s54, v9
	ds_write_b32 v159, v161 offset:0
	ds_write_b128 v8, v[72:75] offset:0
	s_sleep 1
	ds_write_b128 v8, v[76:79] offset:128
	ds_write_b128 v8, v[80:83] offset:256
	s_sleep 1
	ds_write_b128 v8, v[84:87] offset:384
	ds_write2_b32 v138, v96, v97 offset0:1 offset1:3
	s_sleep 1
	ds_write2_b32 v139, v88, v89 offset0:0 offset1:2
	ds_write2_b32 v138, v98, v99 offset0:65 offset1:67
	s_sleep 1
	ds_write2_b32 v139, v90, v91 offset0:64 offset1:66
	ds_write2_b32 v138, v100, v101 offset0:33 offset1:35
	s_sleep 1
	ds_write2_b32 v139, v92, v93 offset0:32 offset1:34
	ds_write2_b32 v138, v102, v103 offset0:97 offset1:99
	s_sleep 1
	ds_write2_b32 v139, v94, v95 offset0:96 offset1:98
	ds_write2_b32 v142, v104, v105 offset1:36
	s_sleep 1
	s_cmp_lg_u32 s7, 4
	s_cbranch_scc1 .Lsc_nokb1
	s_and_saveexec_b64 s[68:69], s[12:13]
	ds_write_b128 v158, v[88:91] offset:0
	ds_write_b128 v158, v[92:95] offset:128
	s_mov_b64 exec, s[68:69]

.Lsc_gf_go2:
	ds_read_b32 v185, v183
	ds_read_b32 v186, v183 offset:256
	ds_read_b32 v187, v183 offset:512
	s_waitcnt lgkmcnt(0)
	v_and_b32_e32 v185, v174, v185
	v_and_b32_e32 v186, v175, v186
	v_and_b32_e32 v187, v176, v187
	v_add_f32_e32 v185, v185, v186
	v_add_f32_e32 v185, v185, v187
	v_fma_f32 v124, v124, s14, v185
	v_fma_f32 v125, v125, s14, v185
	v_fma_f32 v126, v126, s14, v185
	v_fma_f32 v127, v127, s14, v185
	v_fma_f32 v128, v128, s14, v185
	v_fma_f32 v129, v129, s14, v185
	v_fma_f32 v130, v130, s14, v185
	v_fma_f32 v131, v131, s14, v185
	v_exp_f32_e64 v188, -v185
	v_exp_f32_e64 v124, -v124
	v_exp_f32_e64 v125, -v125
	v_exp_f32_e64 v126, -v126
	v_exp_f32_e64 v127, -v127
	v_exp_f32_e64 v128, -v128
	v_exp_f32_e64 v129, -v129
	v_exp_f32_e64 v130, -v130
	v_exp_f32_e64 v131, -v131
	s_nop 0
	ds_write_b32 v155, v188
	ds_write_b32 v155, v124 offset:256
	ds_write_b32 v155, v125 offset:512
	ds_write_b32 v155, v126 offset:768
	ds_write_b32 v155, v127 offset:1024
	ds_write_b32 v155, v128 offset:1280
	ds_write_b32 v155, v129 offset:1536
	ds_write_b32 v155, v130 offset:1792
	ds_write_b32 v155, v131 offset:2048
	v_mov_b32_e32 v161, v131
	s_waitcnt lgkmcnt(0)
	ds_read_b128 v[64:67], v153 offset:2048
	ds_read_b128 v[68:71], v153 offset:2176
	ds_read_b128 v[116:119], v153 offset:2304
	ds_read_b128 v[120:123], v153 offset:2432
	s_waitcnt lgkmcnt(0)
	v_rcp_f32_e32 v124, v116
	v_rcp_f32_e32 v125, v117
	v_rcp_f32_e32 v126, v118
	v_rcp_f32_e32 v127, v119
	v_rcp_f32_e32 v128, v120
	v_rcp_f32_e32 v129, v121
	v_rcp_f32_e32 v130, v122
	v_rcp_f32_e32 v131, v123
	s_nop 1
	v_pk_mul_f32 v[72:73], v[72:73], v[124:125]
	v_pk_mul_f32 v[80:81], v[80:81], v[124:125]
	v_pk_mul_f32 v[88:89], v[88:89], v[64:65]
	v_pk_mul_f32 v[96:97], v[96:97], v[116:117]
	v_pk_mul_f32 v[74:75], v[74:75], v[126:127]
	v_pk_mul_f32 v[82:83], v[82:83], v[126:127]
	v_pk_mul_f32 v[90:91], v[90:91], v[66:67]
	v_pk_mul_f32 v[98:99], v[98:99], v[118:119]
	v_pk_mul_f32 v[76:77], v[76:77], v[128:129]
	v_pk_mul_f32 v[84:85], v[84:85], v[128:129]
	v_pk_mul_f32 v[92:93], v[92:93], v[68:69]
	v_pk_mul_f32 v[100:101], v[100:101], v[120:121]
	v_pk_mul_f32 v[78:79], v[78:79], v[130:131]
	v_pk_mul_f32 v[86:87], v[86:87], v[130:131]
	v_pk_mul_f32 v[94:95], v[94:95], v[70:71]
	v_pk_mul_f32 v[102:103], v[102:103], v[122:123]
	global_load_dwordx2 v[46:47], v5, s[36:37]
	global_load_dwordx2 v[48:49], v5, s[36:37] offset:64
	global_load_dwordx2 v[50:51], v5, s[38:39]
	global_load_dwordx2 v[52:53], v5, s[38:39] offset:64
	global_load_dwordx2 v[54:55], v5, s[40:41]
	global_load_dwordx2 v[56:57], v5, s[40:41] offset:64
	global_load_dwordx2 v[58:59], v5, s[42:43]
	global_load_dwordx2 v[60:61], v5, s[42:43] offset:64
	global_load_dword v62, v6, s[46:47]
	global_load_dword v63, v9, s[44:45]
	v_add_u32_e32 v5, s54, v5
	v_add_u32_e32 v6, s55, v6
	v_add_u32_e32 v9, s54, v9
	ds_write_b32 v159, v161 offset:34816
	ds_write_b128 v8, v[72:75] offset:34816
	s_sleep 1
	ds_write_b128 v8, v[76:79] offset:34944
	ds_write_b128 v8, v[80:83] offset:35072
	s_sleep 1
	ds_write_b128 v8, v[84:87] offset:35200
	ds_write2_b32 v140, v96, v97 offset0:1 offset1:3
	s_sleep 1
	ds_write2_b32 v141, v88, v89 offset0:0 offset1:2
	ds_write2_b32 v140, v98, v99 offset0:65 offset1:67
	s_sleep 1
	ds_write2_b32 v141, v90, v91 offset0:64 offset1:66
	ds_write2_b32 v140, v100, v101 offset0:33 offset1:35
	s_sleep 1
	ds_write2_b32 v141, v92, v93 offset0:32 offset1:34
	ds_write2_b32 v140, v102, v103 offset0:97 offset1:99
	s_sleep 1
	ds_write2_b32 v141, v94, v95 offset0:96 offset1:98
	ds_write2_b32 v143, v104, v105 offset1:36
	s_sleep 1
	s_cmp_lg_u32 s7, 4
	s_cbranch_scc1 .Lsc_nokb2
	s_and_saveexec_b64 s[68:69], s[12:13]
	ds_write_b128 v158, v[88:91] offset:34816
	ds_write_b128 v158, v[92:95] offset:34944
	s_mov_b64 exec, s[68:69]

.Lsc_G_gom0:
	ds_write_b32 v159, v161 offset:0
	ds_write_b128 v8, v[72:75] offset:0
	s_sleep 1
	ds_write_b128 v8, v[76:79] offset:128
	ds_write_b128 v8, v[80:83] offset:256
	s_sleep 1
	ds_write_b128 v8, v[84:87] offset:384
	ds_write2_b32 v138, v96, v97 offset0:1 offset1:3
	s_sleep 1
	ds_write2_b32 v139, v88, v89 offset0:0 offset1:2
	ds_write2_b32 v138, v98, v99 offset0:65 offset1:67
	s_sleep 1
	ds_write2_b32 v139, v90, v91 offset0:64 offset1:66
	ds_write2_b32 v138, v100, v101 offset0:33 offset1:35
	s_sleep 1
	ds_write2_b32 v139, v92, v93 offset0:32 offset1:34
	ds_write2_b32 v138, v102, v103 offset0:97 offset1:99
	s_sleep 1
	ds_write2_b32 v139, v94, v95 offset0:96 offset1:98
	ds_write2_b32 v142, v104, v105 offset1:36
	s_sleep 1
	s_cmp_lg_u32 s7, 4
	s_cbranch_scc1 .Lsc_nokb3
	s_and_saveexec_b64 s[68:69], s[12:13]
	ds_write_b128 v158, v[88:91] offset:0
	ds_write_b128 v158, v[92:95] offset:128
	s_mov_b64 exec, s[68:69]
.Lsc_nokb3:
	ds_read_b128 v[106:109], v2 offset:0
	ds_read_b128 v[122:125], v2 offset:16384
	s_sleep 1
	ds_read_b128 v[110:113], v3 offset:0
	ds_read_b128 v[126:129], v3 offset:16384
	s_sleep 1
	ds_read_b128 v[114:117], v4 offset:0
	ds_read_b128 v[130:133], v4 offset:16384
	s_sleep 1
	ds_read_b128 v[118:121], v10 offset:0
	ds_read_b128 v[134:137], v10 offset:16384
	s_sleep 1
	s_waitcnt lgkmcnt(0)
	v_pk_add_f32 v[106:107], v[106:107], v[108:109]
	v_pk_add_f32 v[110:111], v[110:111], v[112:113]
	v_pk_add_f32 v[114:115], v[114:115], v[116:117]
	v_pk_add_f32 v[118:119], v[118:119], v[120:121]
	v_pk_add_f32 v[106:107], v[106:107], v[110:111]
	v_pk_add_f32 v[114:115], v[114:115], v[118:119]
	v_pk_add_f32 v[106:107], v[106:107], v[114:115]
	v_add_f32_e32 v64, v106, v107
	v_pk_add_f32 v[122:123], v[122:123], v[124:125]
	v_pk_add_f32 v[126:127], v[126:127], v[128:129]
	v_pk_add_f32 v[130:131], v[130:131], v[132:133]
	v_pk_add_f32 v[134:135], v[134:135], v[136:137]
	v_pk_add_f32 v[122:123], v[122:123], v[126:127]
	v_pk_add_f32 v[130:131], v[130:131], v[134:135]
	v_pk_add_f32 v[122:123], v[122:123], v[130:131]
	v_add_f32_e32 v65, v122, v123
	global_store_dword v7, v64, s[48:49]
	global_store_dword v165, v65, s[48:49]
	v_add_u32_e32 v7, s64, v7
	v_add_u32_e32 v165, s64, v165
	s_add_i32 s6, s6, 1
	v_add_u32_e32 v146, 1, v146
	s_waitcnt lgkmcnt(0)
	ds_write_b32 v145, v146
	s_waitcnt vmcnt(10)
	v_lshlrev_b32_e32 v64, 16, v54
	v_and_b32_e32 v65, 0xffff0000, v54
	v_lshlrev_b32_e32 v66, 16, v55
	v_and_b32_e32 v67, 0xffff0000, v55
	v_lshlrev_b32_e32 v68, 16, v56
	v_and_b32_e32 v69, 0xffff0000, v56
	v_lshlrev_b32_e32 v70, 16, v57
	v_and_b32_e32 v71, 0xffff0000, v57
	ds_write_b128 v153, v[64:67]
	ds_write_b128 v153, v[68:71] offset:128
	s_waitcnt lgkmcnt(0)
	ds_read_b32 v124, v154 offset:0
	ds_read_b32 v125, v154 offset:256
	ds_read_b32 v126, v154 offset:512
	ds_read_b32 v127, v154 offset:768
	ds_read_b32 v128, v154 offset:1024
	ds_read_b32 v129, v154 offset:1280
	ds_read_b32 v130, v154 offset:1536
	ds_read_b32 v131, v154 offset:1792
	v_lshlrev_b32_e32 v108, 16, v50
	v_and_b32_e32 v109, 0xffff0000, v50
	v_lshlrev_b32_e32 v110, 16, v58
	v_and_b32_e32 v111, 0xffff0000, v58
	v_lshlrev_b32_e32 v96, 16, v46
	v_and_b32_e32 v97, 0xffff0000, v46
	v_pk_mul_f32 v[114:115], v[12:13], v[108:109]
	v_pk_fma_f32 v[112:113], v[20:21], v[110:111], v[190:191]
	v_pk_mul_f32 v[88:89], v[62:63], v[114:115] op_sel_hi:[0,1]
	v_pk_mul_f32 v[72:73], v[112:113], v[108:109]
	v_pk_mul_f32 v[80:81], v[88:89], v[110:111]
	v_lshlrev_b32_e32 v108, 16, v51
	v_and_b32_e32 v109, 0xffff0000, v51
	v_lshlrev_b32_e32 v110, 16, v59
	v_and_b32_e32 v111, 0xffff0000, v59
	v_lshlrev_b32_e32 v98, 16, v47
	v_and_b32_e32 v99, 0xffff0000, v47
	v_pk_mul_f32 v[114:115], v[14:15], v[108:109]
	v_pk_fma_f32 v[112:113], v[22:23], v[110:111], v[192:193]
	v_pk_mul_f32 v[90:91], v[62:63], v[114:115] op_sel_hi:[0,1]
	v_pk_mul_f32 v[74:75], v[112:113], v[108:109]
	v_pk_mul_f32 v[82:83], v[90:91], v[110:111]
	v_lshlrev_b32_e32 v108, 16, v52
	v_and_b32_e32 v109, 0xffff0000, v52
	v_lshlrev_b32_e32 v110, 16, v60
	v_and_b32_e32 v111, 0xffff0000, v60
	v_lshlrev_b32_e32 v100, 16, v48
	v_and_b32_e32 v101, 0xffff0000, v48
	v_pk_mul_f32 v[114:115], v[16:17], v[108:109]
	v_pk_fma_f32 v[112:113], v[24:25], v[110:111], v[194:195]
	v_pk_mul_f32 v[92:93], v[62:63], v[114:115] op_sel_hi:[0,1]
	v_pk_mul_f32 v[76:77], v[112:113], v[108:109]
	v_pk_mul_f32 v[84:85], v[92:93], v[110:111]
	v_lshlrev_b32_e32 v108, 16, v53
	v_and_b32_e32 v109, 0xffff0000, v53
	v_lshlrev_b32_e32 v110, 16, v61
	v_and_b32_e32 v111, 0xffff0000, v61
	v_lshlrev_b32_e32 v102, 16, v49
	v_and_b32_e32 v103, 0xffff0000, v49
	v_pk_mul_f32 v[114:115], v[18:19], v[108:109]
	v_pk_fma_f32 v[112:113], v[26:27], v[110:111], v[196:197]
	v_pk_mul_f32 v[94:95], v[62:63], v[114:115] op_sel_hi:[0,1]
	v_pk_mul_f32 v[78:79], v[112:113], v[108:109]
	v_pk_mul_f32 v[86:87], v[94:95], v[110:111]
	v_lshlrev_b32_e32 v104, 16, v63
	v_and_b32_e32 v105, 0xffff0000, v63
	s_waitcnt lgkmcnt(0)
	v_add_f32_e32 v125, v124, v125
	v_add_f32_e32 v126, v125, v126
	v_add_f32_e32 v127, v126, v127
	v_add_f32_e32 v128, v127, v128
	v_add_f32_e32 v129, v128, v129
	v_add_f32_e32 v130, v129, v130
	v_add_f32_e32 v131, v130, v131
	s_and_b32 s72, s6, 3
	s_lshl_b32 s72, s72, 10
	v_add_u32_e32 v182, s72, v180
	v_add_u32_e32 v183, s72, v181
	v_mul_f32_e32 v189, 0x3fb8aa3b, v131
	ds_write_b32 v182, v189
	v_add_u32_e32 v184, 1, v146
	s_waitcnt lgkmcnt(0)
	ds_write_b32 v162, v184
	s_add_u32 s73, s6, 1
	s_mov_b32 s69, 0x100000

.Lsc_G_gom1:
	ds_write_b32 v159, v161 offset:34816
	ds_write_b128 v8, v[72:75] offset:34816
	s_sleep 1
	ds_write_b128 v8, v[76:79] offset:34944
	ds_write_b128 v8, v[80:83] offset:35072
	s_sleep 1
	ds_write_b128 v8, v[84:87] offset:35200
	ds_write2_b32 v140, v96, v97 offset0:1 offset1:3
	s_sleep 1
	ds_write2_b32 v141, v88, v89 offset0:0 offset1:2
	ds_write2_b32 v140, v98, v99 offset0:65 offset1:67
	s_sleep 1
	ds_write2_b32 v141, v90, v91 offset0:64 offset1:66
	ds_write2_b32 v140, v100, v101 offset0:33 offset1:35
	s_sleep 1
	ds_write2_b32 v141, v92, v93 offset0:32 offset1:34
	ds_write2_b32 v140, v102, v103 offset0:97 offset1:99
	s_sleep 1
	ds_write2_b32 v141, v94, v95 offset0:96 offset1:98
	ds_write2_b32 v143, v104, v105 offset1:36
	s_sleep 1
	s_cmp_lg_u32 s7, 4
	s_cbranch_scc1 .Lsc_nokb4
	s_and_saveexec_b64 s[68:69], s[12:13]
	ds_write_b128 v158, v[88:91] offset:34816
	ds_write_b128 v158, v[92:95] offset:34944
	s_mov_b64 exec, s[68:69]
.Lsc_nokb4:
	ds_read_b128 v[106:109], v2 offset:32768
	ds_read_b128 v[122:125], v2 offset:49152
	s_sleep 1
	ds_read_b128 v[110:113], v3 offset:32768
	ds_read_b128 v[126:129], v3 offset:49152
	s_sleep 1
	ds_read_b128 v[114:117], v4 offset:32768
	ds_read_b128 v[130:133], v4 offset:49152
	s_sleep 1
	ds_read_b128 v[118:121], v10 offset:32768
	ds_read_b128 v[134:137], v10 offset:49152
	s_sleep 1
	s_waitcnt lgkmcnt(0)
	v_pk_add_f32 v[106:107], v[106:107], v[108:109]
	v_pk_add_f32 v[110:111], v[110:111], v[112:113]
	v_pk_add_f32 v[114:115], v[114:115], v[116:117]
	v_pk_add_f32 v[118:119], v[118:119], v[120:121]
	v_pk_add_f32 v[106:107], v[106:107], v[110:111]
	v_pk_add_f32 v[114:115], v[114:115], v[118:119]
	v_pk_add_f32 v[106:107], v[106:107], v[114:115]
	v_add_f32_e32 v64, v106, v107
	v_pk_add_f32 v[122:123], v[122:123], v[124:125]
	v_pk_add_f32 v[126:127], v[126:127], v[128:129]
	v_pk_add_f32 v[130:131], v[130:131], v[132:133]
	v_pk_add_f32 v[134:135], v[134:135], v[136:137]
	v_pk_add_f32 v[122:123], v[122:123], v[126:127]
	v_pk_add_f32 v[130:131], v[130:131], v[134:135]
	v_pk_add_f32 v[122:123], v[122:123], v[130:131]
	v_add_f32_e32 v65, v122, v123
	global_store_dword v7, v64, s[48:49]
	global_store_dword v165, v65, s[48:49]
	v_add_u32_e32 v7, s64, v7
	v_add_u32_e32 v165, s64, v165
	s_add_i32 s6, s6, 1
	v_add_u32_e32 v146, 1, v146
	s_waitcnt lgkmcnt(0)
	ds_write_b32 v145, v146
	s_cmp_lt_u32 s6, 0xfe
	s_cbranch_scc1 .Lsc_G_loop
	s_waitcnt vmcnt(10)
	v_lshlrev_b32_e32 v64, 16, v36
	v_and_b32_e32 v65, 0xffff0000, v36
	v_lshlrev_b32_e32 v66, 16, v37
	v_and_b32_e32 v67, 0xffff0000, v37
	v_lshlrev_b32_e32 v68, 16, v38
	v_and_b32_e32 v69, 0xffff0000, v38
	v_lshlrev_b32_e32 v70, 16, v39
	v_and_b32_e32 v71, 0xffff0000, v39
	ds_write_b128 v153, v[64:67]
	ds_write_b128 v153, v[68:71] offset:128
	s_waitcnt lgkmcnt(0)
	ds_read_b32 v124, v154 offset:0
	ds_read_b32 v125, v154 offset:256
	ds_read_b32 v126, v154 offset:512
	ds_read_b32 v127, v154 offset:768
	ds_read_b32 v128, v154 offset:1024
	ds_read_b32 v129, v154 offset:1280
	ds_read_b32 v130, v154 offset:1536
	ds_read_b32 v131, v154 offset:1792
	v_lshlrev_b32_e32 v108, 16, v32
	v_and_b32_e32 v109, 0xffff0000, v32
	v_lshlrev_b32_e32 v110, 16, v40
	v_and_b32_e32 v111, 0xffff0000, v40
	v_lshlrev_b32_e32 v96, 16, v28
	v_and_b32_e32 v97, 0xffff0000, v28
	v_pk_mul_f32 v[114:115], v[12:13], v[108:109]
	v_pk_fma_f32 v[112:113], v[20:21], v[110:111], v[190:191]
	v_pk_mul_f32 v[88:89], v[44:45], v[114:115] op_sel_hi:[0,1]
	v_pk_mul_f32 v[72:73], v[112:113], v[108:109]
	v_pk_mul_f32 v[80:81], v[88:89], v[110:111]
	v_lshlrev_b32_e32 v108, 16, v33
	v_and_b32_e32 v109, 0xffff0000, v33
	v_lshlrev_b32_e32 v110, 16, v41
	v_and_b32_e32 v111, 0xffff0000, v41
	v_lshlrev_b32_e32 v98, 16, v29
	v_and_b32_e32 v99, 0xffff0000, v29
	v_pk_mul_f32 v[114:115], v[14:15], v[108:109]
	v_pk_fma_f32 v[112:113], v[22:23], v[110:111], v[192:193]
	v_pk_mul_f32 v[90:91], v[44:45], v[114:115] op_sel_hi:[0,1]
	v_pk_mul_f32 v[74:75], v[112:113], v[108:109]
	v_pk_mul_f32 v[82:83], v[90:91], v[110:111]
	v_lshlrev_b32_e32 v108, 16, v34
	v_and_b32_e32 v109, 0xffff0000, v34
	v_lshlrev_b32_e32 v110, 16, v42
	v_and_b32_e32 v111, 0xffff0000, v42
	v_lshlrev_b32_e32 v100, 16, v30
	v_and_b32_e32 v101, 0xffff0000, v30
	v_pk_mul_f32 v[114:115], v[16:17], v[108:109]
	v_pk_fma_f32 v[112:113], v[24:25], v[110:111], v[194:195]
	v_pk_mul_f32 v[92:93], v[44:45], v[114:115] op_sel_hi:[0,1]
	v_pk_mul_f32 v[76:77], v[112:113], v[108:109]
	v_pk_mul_f32 v[84:85], v[92:93], v[110:111]
	v_lshlrev_b32_e32 v108, 16, v35
	v_and_b32_e32 v109, 0xffff0000, v35
	v_lshlrev_b32_e32 v110, 16, v43
	v_and_b32_e32 v111, 0xffff0000, v43
	v_lshlrev_b32_e32 v102, 16, v31
	v_and_b32_e32 v103, 0xffff0000, v31
	v_pk_mul_f32 v[114:115], v[18:19], v[108:109]
	v_pk_fma_f32 v[112:113], v[26:27], v[110:111], v[196:197]
	v_pk_mul_f32 v[94:95], v[44:45], v[114:115] op_sel_hi:[0,1]
	v_pk_mul_f32 v[78:79], v[112:113], v[108:109]
	v_pk_mul_f32 v[86:87], v[94:95], v[110:111]
	v_lshlrev_b32_e32 v104, 16, v45
	v_and_b32_e32 v105, 0xffff0000, v45
	s_waitcnt lgkmcnt(0)
	v_add_f32_e32 v125, v124, v125
	v_add_f32_e32 v126, v125, v126
	v_add_f32_e32 v127, v126, v127
	v_add_f32_e32 v128, v127, v128
	v_add_f32_e32 v129, v128, v129
	v_add_f32_e32 v130, v129, v130
	v_add_f32_e32 v131, v130, v131
	s_and_b32 s72, s6, 3
	s_lshl_b32 s72, s72, 10
	v_add_u32_e32 v182, s72, v180
	v_add_u32_e32 v183, s72, v181
	v_mul_f32_e32 v189, 0x3fb8aa3b, v131
	ds_write_b32 v182, v189
	v_add_u32_e32 v184, 1, v146
	s_waitcnt lgkmcnt(0)
	ds_write_b32 v162, v184
	s_add_u32 s73, s6, 1
	s_mov_b32 s69, 0x100000

.Lsc_nokb5:
	ds_read_b128 v[106:109], v2 offset:0
	ds_read_b128 v[122:125], v2 offset:16384
	s_sleep 1
	ds_read_b128 v[110:113], v3 offset:0
	ds_read_b128 v[126:129], v3 offset:16384
	s_sleep 1
	ds_read_b128 v[114:117], v4 offset:0
	ds_read_b128 v[130:133], v4 offset:16384
	s_sleep 1
	ds_read_b128 v[118:121], v10 offset:0
	ds_read_b128 v[134:137], v10 offset:16384
	s_sleep 1
	s_waitcnt lgkmcnt(0)
	v_pk_add_f32 v[106:107], v[106:107], v[108:109]
	v_pk_add_f32 v[110:111], v[110:111], v[112:113]
	v_pk_add_f32 v[114:115], v[114:115], v[116:117]
	v_pk_add_f32 v[118:119], v[118:119], v[120:121]
	v_pk_add_f32 v[106:107], v[106:107], v[110:111]
	v_pk_add_f32 v[114:115], v[114:115], v[118:119]
	v_pk_add_f32 v[106:107], v[106:107], v[114:115]
	v_add_f32_e32 v64, v106, v107
	v_pk_add_f32 v[122:123], v[122:123], v[124:125]
	v_pk_add_f32 v[126:127], v[126:127], v[128:129]
	v_pk_add_f32 v[130:131], v[130:131], v[132:133]
	v_pk_add_f32 v[134:135], v[134:135], v[136:137]
	v_pk_add_f32 v[122:123], v[122:123], v[126:127]
	v_pk_add_f32 v[130:131], v[130:131], v[134:135]
	v_pk_add_f32 v[122:123], v[122:123], v[130:131]
	v_add_f32_e32 v65, v122, v123
	global_store_dword v7, v64, s[48:49]
	global_store_dword v165, v65, s[48:49]
	v_add_u32_e32 v7, s64, v7
	v_add_u32_e32 v165, s64, v165
	s_add_i32 s6, s6, 1
	v_add_u32_e32 v146, 1, v146
	s_waitcnt lgkmcnt(0)
	ds_write_b32 v145, v146
	s_waitcnt vmcnt(0)
	v_lshlrev_b32_e32 v64, 16, v54
	v_and_b32_e32 v65, 0xffff0000, v54
	v_lshlrev_b32_e32 v66, 16, v55
	v_and_b32_e32 v67, 0xffff0000, v55
	v_lshlrev_b32_e32 v68, 16, v56
	v_and_b32_e32 v69, 0xffff0000, v56
	v_lshlrev_b32_e32 v70, 16, v57
	v_and_b32_e32 v71, 0xffff0000, v57
	ds_write_b128 v153, v[64:67]
	ds_write_b128 v153, v[68:71] offset:128
	s_waitcnt lgkmcnt(0)
	ds_read_b32 v124, v154 offset:0
	ds_read_b32 v125, v154 offset:256
	ds_read_b32 v126, v154 offset:512
	ds_read_b32 v127, v154 offset:768
	ds_read_b32 v128, v154 offset:1024
	ds_read_b32 v129, v154 offset:1280
	ds_read_b32 v130, v154 offset:1536
	ds_read_b32 v131, v154 offset:1792
	v_lshlrev_b32_e32 v108, 16, v50
	v_and_b32_e32 v109, 0xffff0000, v50
	v_lshlrev_b32_e32 v110, 16, v58
	v_and_b32_e32 v111, 0xffff0000, v58
	v_lshlrev_b32_e32 v96, 16, v46
	v_and_b32_e32 v97, 0xffff0000, v46
	v_pk_mul_f32 v[114:115], v[12:13], v[108:109]
	v_pk_fma_f32 v[112:113], v[20:21], v[110:111], v[190:191]
	v_pk_mul_f32 v[88:89], v[62:63], v[114:115] op_sel_hi:[0,1]
	v_pk_mul_f32 v[72:73], v[112:113], v[108:109]
	v_pk_mul_f32 v[80:81], v[88:89], v[110:111]
	v_lshlrev_b32_e32 v108, 16, v51
	v_and_b32_e32 v109, 0xffff0000, v51
	v_lshlrev_b32_e32 v110, 16, v59
	v_and_b32_e32 v111, 0xffff0000, v59
	v_lshlrev_b32_e32 v98, 16, v47
	v_and_b32_e32 v99, 0xffff0000, v47
	v_pk_mul_f32 v[114:115], v[14:15], v[108:109]
	v_pk_fma_f32 v[112:113], v[22:23], v[110:111], v[192:193]
	v_pk_mul_f32 v[90:91], v[62:63], v[114:115] op_sel_hi:[0,1]
	v_pk_mul_f32 v[74:75], v[112:113], v[108:109]
	v_pk_mul_f32 v[82:83], v[90:91], v[110:111]
	v_lshlrev_b32_e32 v108, 16, v52
	v_and_b32_e32 v109, 0xffff0000, v52
	v_lshlrev_b32_e32 v110, 16, v60
	v_and_b32_e32 v111, 0xffff0000, v60
	v_lshlrev_b32_e32 v100, 16, v48
	v_and_b32_e32 v101, 0xffff0000, v48
	v_pk_mul_f32 v[114:115], v[16:17], v[108:109]
	v_pk_fma_f32 v[112:113], v[24:25], v[110:111], v[194:195]
	v_pk_mul_f32 v[92:93], v[62:63], v[114:115] op_sel_hi:[0,1]
	v_pk_mul_f32 v[76:77], v[112:113], v[108:109]
	v_pk_mul_f32 v[84:85], v[92:93], v[110:111]
	v_lshlrev_b32_e32 v108, 16, v53
	v_and_b32_e32 v109, 0xffff0000, v53
	v_lshlrev_b32_e32 v110, 16, v61
	v_and_b32_e32 v111, 0xffff0000, v61
	v_lshlrev_b32_e32 v102, 16, v49
	v_and_b32_e32 v103, 0xffff0000, v49
	v_pk_mul_f32 v[114:115], v[18:19], v[108:109]
	v_pk_fma_f32 v[112:113], v[26:27], v[110:111], v[196:197]
	v_pk_mul_f32 v[94:95], v[62:63], v[114:115] op_sel_hi:[0,1]
	v_pk_mul_f32 v[78:79], v[112:113], v[108:109]
	v_pk_mul_f32 v[86:87], v[94:95], v[110:111]
	v_lshlrev_b32_e32 v104, 16, v63
	v_and_b32_e32 v105, 0xffff0000, v63
	s_waitcnt lgkmcnt(0)
	v_add_f32_e32 v125, v124, v125
	v_add_f32_e32 v126, v125, v126
	v_add_f32_e32 v127, v126, v127
	v_add_f32_e32 v128, v127, v128
	v_add_f32_e32 v129, v128, v129
	v_add_f32_e32 v130, v129, v130
	v_add_f32_e32 v131, v130, v131
	s_and_b32 s72, s6, 3
	s_lshl_b32 s72, s72, 10
	v_add_u32_e32 v182, s72, v180
	v_add_u32_e32 v183, s72, v181
	v_mul_f32_e32 v189, 0x3fb8aa3b, v131
	ds_write_b32 v182, v189
	v_add_u32_e32 v184, 1, v146
	s_waitcnt lgkmcnt(0)
	ds_write_b32 v162, v184
	s_add_u32 s73, s6, 1
	s_mov_b32 s69, 0x100000

.Lsc_nokb6:
	ds_read_b128 v[106:109], v2 offset:32768
	ds_read_b128 v[122:125], v2 offset:49152
	s_sleep 1
	ds_read_b128 v[110:113], v3 offset:32768
	ds_read_b128 v[126:129], v3 offset:49152
	s_sleep 1
	ds_read_b128 v[114:117], v4 offset:32768
	ds_read_b128 v[130:133], v4 offset:49152
	s_sleep 1
	ds_read_b128 v[118:121], v10 offset:32768
	ds_read_b128 v[134:137], v10 offset:49152
	s_sleep 1
	s_waitcnt lgkmcnt(0)
	v_pk_add_f32 v[106:107], v[106:107], v[108:109]
	v_pk_add_f32 v[110:111], v[110:111], v[112:113]
	v_pk_add_f32 v[114:115], v[114:115], v[116:117]
	v_pk_add_f32 v[118:119], v[118:119], v[120:121]
	v_pk_add_f32 v[106:107], v[106:107], v[110:111]
	v_pk_add_f32 v[114:115], v[114:115], v[118:119]
	v_pk_add_f32 v[106:107], v[106:107], v[114:115]
	v_add_f32_e32 v64, v106, v107
	v_pk_add_f32 v[122:123], v[122:123], v[124:125]
	v_pk_add_f32 v[126:127], v[126:127], v[128:129]
	v_pk_add_f32 v[130:131], v[130:131], v[132:133]
	v_pk_add_f32 v[134:135], v[134:135], v[136:137]
	v_pk_add_f32 v[122:123], v[122:123], v[126:127]
	v_pk_add_f32 v[130:131], v[130:131], v[134:135]
	v_pk_add_f32 v[122:123], v[122:123], v[130:131]
	v_add_f32_e32 v65, v122, v123
	global_store_dword v7, v64, s[48:49]
	global_store_dword v165, v65, s[48:49]
	v_add_u32_e32 v7, s64, v7
	v_add_u32_e32 v165, s64, v165
	s_add_i32 s6, s6, 1
	v_add_u32_e32 v146, 1, v146
	s_waitcnt lgkmcnt(0)
	ds_write_b32 v145, v146
	s_sub_u32 s65, s6, 1
	ds_read_b128 v[148:151], v144
	s_waitcnt lgkmcnt(0)
	v_min_u32_e32 v148, v148, v149
	v_min3_u32 v148, v148, v150, v151
	s_nop 1
	v_readfirstlane_b32 s68, v148
	s_cmp_ge_u32 s68, s65
	s_cbranch_scc1 .Lsc_G_goz2
	s_mov_b32 s69, 0x100000

.Lsc_G_goz2:
	ds_read_b128 v[106:109], v2 offset:0
	ds_read_b128 v[122:125], v2 offset:16384
	s_sleep 1
	ds_read_b128 v[110:113], v3 offset:0
	ds_read_b128 v[126:129], v3 offset:16384
	s_sleep 1
	ds_read_b128 v[114:117], v4 offset:0
	ds_read_b128 v[130:133], v4 offset:16384
	s_sleep 1
	ds_read_b128 v[118:121], v10 offset:0
	ds_read_b128 v[134:137], v10 offset:16384
	s_sleep 1
	s_waitcnt lgkmcnt(0)
	v_pk_add_f32 v[106:107], v[106:107], v[108:109]
	v_pk_add_f32 v[110:111], v[110:111], v[112:113]
	v_pk_add_f32 v[114:115], v[114:115], v[116:117]
	v_pk_add_f32 v[118:119], v[118:119], v[120:121]
	v_pk_add_f32 v[106:107], v[106:107], v[110:111]
	v_pk_add_f32 v[114:115], v[114:115], v[118:119]
	v_pk_add_f32 v[106:107], v[106:107], v[114:115]
	v_add_f32_e32 v64, v106, v107
	v_pk_add_f32 v[122:123], v[122:123], v[124:125]
	v_pk_add_f32 v[126:127], v[126:127], v[128:129]
	v_pk_add_f32 v[130:131], v[130:131], v[132:133]
	v_pk_add_f32 v[134:135], v[134:135], v[136:137]
	v_pk_add_f32 v[122:123], v[122:123], v[126:127]
	v_pk_add_f32 v[130:131], v[130:131], v[134:135]
	v_pk_add_f32 v[122:123], v[122:123], v[130:131]
	v_add_f32_e32 v65, v122, v123
	global_store_dword v7, v64, s[48:49]
	global_store_dword v165, v65, s[48:49]
	v_add_u32_e32 v7, s64, v7
	v_add_u32_e32 v165, s64, v165
	s_add_i32 s6, s6, 1
	v_add_u32_e32 v146, 1, v146
	s_waitcnt lgkmcnt(0)
	ds_write_b32 v145, v146
	s_sub_u32 s65, s6, 1
	ds_read_b128 v[148:151], v144
	s_waitcnt lgkmcnt(0)
	v_min_u32_e32 v148, v148, v149
	v_min3_u32 v148, v148, v150, v151
	s_nop 1
	v_readfirstlane_b32 s68, v148
	s_cmp_ge_u32 s68, s65
	s_cbranch_scc1 .Lsc_G_goz3
	s_mov_b32 s69, 0x100000

.Lsc_G_goz3:
	ds_read_b128 v[106:109], v2 offset:32768
	ds_read_b128 v[122:125], v2 offset:49152
	s_sleep 1
	ds_read_b128 v[110:113], v3 offset:32768
	ds_read_b128 v[126:129], v3 offset:49152
	s_sleep 1
	ds_read_b128 v[114:117], v4 offset:32768
	ds_read_b128 v[130:133], v4 offset:49152
	s_sleep 1
	ds_read_b128 v[118:121], v10 offset:32768
	ds_read_b128 v[134:137], v10 offset:49152
	s_sleep 1
	s_waitcnt lgkmcnt(0)
	v_pk_add_f32 v[106:107], v[106:107], v[108:109]
	v_pk_add_f32 v[110:111], v[110:111], v[112:113]
	v_pk_add_f32 v[114:115], v[114:115], v[116:117]
	v_pk_add_f32 v[118:119], v[118:119], v[120:121]
	v_pk_add_f32 v[106:107], v[106:107], v[110:111]
	v_pk_add_f32 v[114:115], v[114:115], v[118:119]
	v_pk_add_f32 v[106:107], v[106:107], v[114:115]
	v_add_f32_e32 v64, v106, v107
	v_pk_add_f32 v[122:123], v[122:123], v[124:125]
	v_pk_add_f32 v[126:127], v[126:127], v[128:129]
	v_pk_add_f32 v[130:131], v[130:131], v[132:133]
	v_pk_add_f32 v[134:135], v[134:135], v[136:137]
	v_pk_add_f32 v[122:123], v[122:123], v[126:127]
	v_pk_add_f32 v[130:131], v[130:131], v[134:135]
	v_pk_add_f32 v[122:123], v[122:123], v[130:131]
	v_add_f32_e32 v65, v122, v123
	global_store_dword v7, v64, s[48:49]
	global_store_dword v165, v65, s[48:49]
	v_add_u32_e32 v7, s64, v7
	v_add_u32_e32 v165, s64, v165
	s_add_i32 s6, s6, 1
	v_add_u32_e32 v146, 1, v146
	s_waitcnt lgkmcnt(0)
	ds_write_b32 v145, v146
